# code-placement pin: .p2align 6 on the three hot loop heads (P1 K-loop, P4 K-loop, attention task loop)
# baseline (speedup 1.0000x reference)
.LBB0_148:
	s_ashr_i32 s37, s36, 31
	s_lshl_b64 s[0:1], s[36:37], 20
	s_add_u32 s54, s56, s0
	s_addc_u32 s55, s57, s1
	s_and_b64 s[0:1], s[38:39], exec
	s_cselect_b32 s0, s55, s43
	s_cselect_b32 s1, s54, s42
	s_ashr_i32 s35, s34, 31
	s_lshl_b64 s[12:13], s[34:35], 20
	s_add_u32 s58, s72, s12
	s_addc_u32 s59, s73, s13
	s_and_b64 s[12:13], s[38:39], exec
	s_cselect_b32 s12, s59, s75
	s_cselect_b32 s13, s58, s74
	s_add_u32 s42, s42, 0x80080
	s_addc_u32 s43, s43, 0
	s_add_u32 s14, s74, 0x100
	v_mov_b32_e32 v0, 0
	s_addc_u32 s15, s75, 0
	s_mov_b32 s16, -2
	v_mov_b32_e32 v1, v0
	v_mov_b32_e32 v2, v0
	v_mov_b32_e32 v3, v0
	v_mov_b32_e32 v4, v0
	v_mov_b32_e32 v5, v0
	v_mov_b32_e32 v6, v0
	v_mov_b32_e32 v7, v0
	v_mov_b32_e32 v16, v0
	v_mov_b32_e32 v17, v0
	v_mov_b32_e32 v18, v0
	v_mov_b32_e32 v19, v0
	v_mov_b32_e32 v20, v0
	v_mov_b32_e32 v21, v0
	v_mov_b32_e32 v22, v0
	v_mov_b32_e32 v23, v0
	v_mov_b32_e32 v32, v0
	v_mov_b32_e32 v33, v0
	v_mov_b32_e32 v34, v0
	v_mov_b32_e32 v35, v0
	v_mov_b32_e32 v36, v0
	v_mov_b32_e32 v37, v0
	v_mov_b32_e32 v38, v0
	v_mov_b32_e32 v39, v0
	v_mov_b32_e32 v48, v0
	v_mov_b32_e32 v49, v0
	v_mov_b32_e32 v50, v0
	v_mov_b32_e32 v51, v0
	v_mov_b32_e32 v52, v0
	v_mov_b32_e32 v53, v0
	v_mov_b32_e32 v54, v0
	v_mov_b32_e32 v55, v0
	v_mov_b32_e32 v8, v0
	v_mov_b32_e32 v9, v0
	v_mov_b32_e32 v10, v0
	v_mov_b32_e32 v11, v0
	v_mov_b32_e32 v12, v0
	v_mov_b32_e32 v13, v0
	v_mov_b32_e32 v14, v0
	v_mov_b32_e32 v15, v0
	v_mov_b32_e32 v24, v0
	v_mov_b32_e32 v25, v0
	v_mov_b32_e32 v26, v0
	v_mov_b32_e32 v27, v0
	v_mov_b32_e32 v28, v0
	v_mov_b32_e32 v29, v0
	v_mov_b32_e32 v30, v0
	v_mov_b32_e32 v31, v0
	v_mov_b32_e32 v40, v0
	v_mov_b32_e32 v41, v0
	v_mov_b32_e32 v42, v0
	v_mov_b32_e32 v43, v0
	v_mov_b32_e32 v44, v0
	v_mov_b32_e32 v45, v0
	v_mov_b32_e32 v46, v0
	v_mov_b32_e32 v47, v0
	v_mov_b32_e32 v56, v0
	v_mov_b32_e32 v57, v0
	v_mov_b32_e32 v58, v0
	v_mov_b32_e32 v59, v0
	v_mov_b32_e32 v60, v0
	v_mov_b32_e32 v61, v0
	v_mov_b32_e32 v62, v0
	v_mov_b32_e32 v63, v0
	v_mov_b32_e32 v64, v0
	v_mov_b32_e32 v65, v0
	v_mov_b32_e32 v66, v0
	v_mov_b32_e32 v67, v0
	v_mov_b32_e32 v68, v0
	v_mov_b32_e32 v69, v0
	v_mov_b32_e32 v70, v0
	v_mov_b32_e32 v71, v0
	v_mov_b32_e32 v80, v0
	v_mov_b32_e32 v81, v0
	v_mov_b32_e32 v82, v0
	v_mov_b32_e32 v83, v0
	v_mov_b32_e32 v84, v0
	v_mov_b32_e32 v85, v0
	v_mov_b32_e32 v86, v0
	v_mov_b32_e32 v87, v0
	v_mov_b32_e32 v96, v0
	v_mov_b32_e32 v97, v0
	v_mov_b32_e32 v98, v0
	v_mov_b32_e32 v99, v0
	v_mov_b32_e32 v100, v0
	v_mov_b32_e32 v101, v0
	v_mov_b32_e32 v102, v0
	v_mov_b32_e32 v103, v0
	v_mov_b32_e32 v112, v0
	v_mov_b32_e32 v113, v0
	v_mov_b32_e32 v114, v0
	v_mov_b32_e32 v115, v0
	v_mov_b32_e32 v116, v0
	v_mov_b32_e32 v117, v0
	v_mov_b32_e32 v118, v0
	v_mov_b32_e32 v119, v0
	v_mov_b32_e32 v72, v0
	v_mov_b32_e32 v73, v0
	v_mov_b32_e32 v74, v0
	v_mov_b32_e32 v75, v0
	v_mov_b32_e32 v76, v0
	v_mov_b32_e32 v77, v0
	v_mov_b32_e32 v78, v0
	v_mov_b32_e32 v79, v0
	v_mov_b32_e32 v88, v0
	v_mov_b32_e32 v89, v0
	v_mov_b32_e32 v90, v0
	v_mov_b32_e32 v91, v0
	v_mov_b32_e32 v92, v0
	v_mov_b32_e32 v93, v0
	v_mov_b32_e32 v94, v0
	v_mov_b32_e32 v95, v0
	v_mov_b32_e32 v104, v0
	v_mov_b32_e32 v105, v0
	v_mov_b32_e32 v106, v0
	v_mov_b32_e32 v107, v0
	v_mov_b32_e32 v108, v0
	v_mov_b32_e32 v109, v0
	v_mov_b32_e32 v110, v0
	v_mov_b32_e32 v111, v0
	v_mov_b32_e32 v120, v0
	v_mov_b32_e32 v121, v0
	v_mov_b32_e32 v122, v0
	v_mov_b32_e32 v123, v0
	v_mov_b32_e32 v124, v0
	v_mov_b32_e32 v125, v0
	v_mov_b32_e32 v126, v0
	v_mov_b32_e32 v127, v0
	.p2align	6

.LBB0_343:
	s_or_b64 exec, exec, s[18:19]
	s_xor_b64 s[12:13], s[56:57], -1
	s_mov_b32 s0, 1
	s_mov_b64 s[56:57], 0
	s_and_b64 vcc, exec, s[12:13]
	s_cbranch_vccnz .LBB0_341
	.p2align	6

.LBB0_660:
	s_add_u32 s47, s22, 0x100
	s_addc_u32 s48, s23, 0
	s_ashr_i32 s17, s16, 31
	s_lshl_b64 s[18:19], s[16:17], 20
	s_add_u32 s20, s30, s18
	s_addc_u32 s21, s31, s19
	s_and_b64 s[18:19], s[4:5], exec
	s_cselect_b32 s17, s21, s11
	s_cselect_b32 s49, s20, s10
	s_ashr_i32 s15, s14, 31
	s_lshl_b64 s[18:19], s[14:15], 20
	s_add_u32 s18, s34, s18
	s_addc_u32 s19, s35, s19
	s_and_b64 s[24:25], s[4:5], exec
	s_cselect_b32 s15, s19, s23
	s_cselect_b32 s50, s18, s22
	v_lshl_add_u64 v[140:141], s[10:11], 0, v[132:133]
	v_lshl_add_u64 v[142:143], s[10:11], 0, v[134:135]
	s_mov_b32 s51, -2
	s_mov_b64 s[22:23], 0
	.p2align	6
